# weight conversion (transpose items): all 8 row loads + gain loads issued before one wait (was 8-16 serialized HBM round trips per item)
# baseline (speedup 1.0000x reference)
.LBB0_20:
	s_waitcnt vmcnt(0)
	v_pk_mul_f32 v[100:101], v[100:101], v[132:133] op_sel_hi:[1,0]
	v_pk_mul_f32 v[102:103], v[102:103], v[132:133] op_sel_hi:[1,0]
	v_pk_mul_f32 v[104:105], v[104:105], v[134:135] op_sel_hi:[1,0]
	v_pk_mul_f32 v[106:107], v[106:107], v[134:135] op_sel_hi:[1,0]
	v_pk_mul_f32 v[108:109], v[108:109], v[136:137] op_sel_hi:[1,0]
	v_pk_mul_f32 v[110:111], v[110:111], v[136:137] op_sel_hi:[1,0]
	v_pk_mul_f32 v[112:113], v[112:113], v[138:139] op_sel_hi:[1,0]
	v_pk_mul_f32 v[114:115], v[114:115], v[138:139] op_sel_hi:[1,0]
	v_pk_mul_f32 v[116:117], v[116:117], v[140:141] op_sel_hi:[1,0]
	v_pk_mul_f32 v[118:119], v[118:119], v[140:141] op_sel_hi:[1,0]
	v_pk_mul_f32 v[120:121], v[120:121], v[142:143] op_sel_hi:[1,0]
	v_pk_mul_f32 v[122:123], v[122:123], v[142:143] op_sel_hi:[1,0]
	v_pk_mul_f32 v[124:125], v[124:125], v[144:145] op_sel_hi:[1,0]
	v_pk_mul_f32 v[126:127], v[126:127], v[144:145] op_sel_hi:[1,0]
	v_pk_mul_f32 v[128:129], v[128:129], v[146:147] op_sel_hi:[1,0]
	v_pk_mul_f32 v[130:131], v[130:131], v[146:147] op_sel_hi:[1,0]
	ds_write2_b32 v31, v100, v101 offset1:1
	ds_write2_b32 v31, v102, v103 offset0:2 offset1:3
	v_add_u32_e32 v2, 0x420, v31
	ds_write2_b32 v2, v104, v105 offset1:1
	ds_write2_b32 v2, v106, v107 offset0:2 offset1:3
	v_add_u32_e32 v2, 0x840, v31
	ds_write2_b32 v2, v108, v109 offset1:1
	ds_write2_b32 v2, v110, v111 offset0:2 offset1:3
	v_add_u32_e32 v2, 0xc60, v31
	ds_write2_b32 v2, v112, v113 offset1:1
	ds_write2_b32 v2, v114, v115 offset0:2 offset1:3
	v_add_u32_e32 v2, 0x1080, v31
	ds_write2_b32 v2, v116, v117 offset1:1
	ds_write2_b32 v2, v118, v119 offset0:2 offset1:3
	v_add_u32_e32 v2, 0x14a0, v31
	ds_write2_b32 v2, v120, v121 offset1:1
	ds_write2_b32 v2, v122, v123 offset0:2 offset1:3
	v_add_u32_e32 v2, 0x18c0, v31
	ds_write2_b32 v2, v124, v125 offset1:1
	ds_write2_b32 v2, v126, v127 offset0:2 offset1:3
	v_add_u32_e32 v2, 0x1ce0, v31
	ds_write2_b32 v2, v128, v129 offset1:1
	ds_write2_b32 v2, v130, v131 offset0:2 offset1:3
	s_waitcnt lgkmcnt(0)
	ds_read2_b32 v[4:5], v30 offset0:33 offset1:41
	ds_read2_b32 v[18:19], v30 offset1:8
	ds_read2_b32 v[20:21], v30 offset0:66 offset1:74
	ds_read2_b32 v[32:33], v30 offset0:99 offset1:107
	ds_read2_b32 v[34:35], v30 offset0:132 offset1:140
	ds_read2_b32 v[36:37], v30 offset0:165 offset1:173
	ds_read2_b32 v[38:39], v30 offset0:198 offset1:206
	ds_read2_b32 v[40:41], v30 offset0:231 offset1:239
	v_add_u32_e32 v42, s31, v15
	v_ashrrev_i32_e32 v43, 31, v42
	s_ashr_i32 s19, s18, 31
	v_lshlrev_b64 v[44:45], 11, v[42:43]
	v_lshl_add_u64 v[44:45], s[16:17], 0, v[44:45]
	s_lshl_b64 s[6:7], s[18:19], 1
	v_lshl_add_u64 v[44:45], v[44:45], 0, s[6:7]
	v_mov_b32_e32 v17, v3
	s_waitcnt lgkmcnt(6)
	v_cvt_pk_bf16_f32 v10, v18, v4
	s_waitcnt lgkmcnt(4)
	v_cvt_pk_bf16_f32 v11, v20, v32
	s_waitcnt lgkmcnt(2)
	v_cvt_pk_bf16_f32 v12, v34, v36
	s_waitcnt lgkmcnt(0)
	v_cvt_pk_bf16_f32 v13, v38, v40
	v_lshl_add_u64 v[44:45], v[44:45], 0, v[16:17]
	v_add_u32_e32 v4, 8, v42
	global_store_dwordx4 v[44:45], v[10:13], off
	s_add_i32 s28, s28, s12
	s_add_i32 s29, s29, s24
	v_cvt_pk_bf16_f32 v10, v19, v5
	v_ashrrev_i32_e32 v5, 31, v4
	v_lshlrev_b64 v[4:5], 11, v[4:5]
	v_lshl_add_u64 v[4:5], s[16:17], 0, v[4:5]
	v_lshl_add_u64 v[4:5], v[4:5], 0, s[6:7]
	v_cvt_pk_bf16_f32 v11, v21, v33
	v_cvt_pk_bf16_f32 v12, v35, v37
	v_cvt_pk_bf16_f32 v13, v39, v41
	v_lshl_add_u64 v[4:5], v[4:5], 0, v[16:17]
	ds_read2_b32 v[18:19], v30 offset0:49 offset1:57
	ds_read2_b32 v[20:21], v30 offset0:16 offset1:24
	ds_read2_b32 v[32:33], v30 offset0:82 offset1:90
	ds_read2_b32 v[34:35], v30 offset0:115 offset1:123
	ds_read2_b32 v[36:37], v30 offset0:148 offset1:156
	ds_read2_b32 v[38:39], v30 offset0:181 offset1:189
	ds_read2_b32 v[40:41], v30 offset0:214 offset1:222
	ds_read2_b32 v[44:45], v30 offset0:247 offset1:255
	global_store_dwordx4 v[4:5], v[10:13], off
	v_add_u32_e32 v4, 16, v42
	v_ashrrev_i32_e32 v5, 31, v4
	v_lshlrev_b64 v[4:5], 11, v[4:5]
	v_lshl_add_u64 v[4:5], s[16:17], 0, v[4:5]
	v_lshl_add_u64 v[4:5], v[4:5], 0, s[6:7]
	s_waitcnt lgkmcnt(6)
	v_cvt_pk_bf16_f32 v10, v20, v18
	s_waitcnt lgkmcnt(4)
	v_cvt_pk_bf16_f32 v11, v32, v34
	s_waitcnt lgkmcnt(2)
	v_cvt_pk_bf16_f32 v12, v36, v38
	s_waitcnt lgkmcnt(0)
	v_cvt_pk_bf16_f32 v13, v40, v44
	v_lshl_add_u64 v[4:5], v[4:5], 0, v[16:17]
	global_store_dwordx4 v[4:5], v[10:13], off
	v_add_u32_e32 v4, 24, v42
	v_ashrrev_i32_e32 v5, 31, v4
	v_lshlrev_b64 v[4:5], 11, v[4:5]
	v_lshl_add_u64 v[4:5], s[16:17], 0, v[4:5]
	v_lshl_add_u64 v[4:5], v[4:5], 0, s[6:7]
	v_cvt_pk_bf16_f32 v10, v21, v19
	v_cvt_pk_bf16_f32 v11, v33, v35
	v_cvt_pk_bf16_f32 v12, v37, v39
	v_cvt_pk_bf16_f32 v13, v41, v45
	v_lshl_add_u64 v[4:5], v[4:5], 0, v[16:17]
	global_store_dwordx4 v[4:5], v[10:13], off
	s_waitcnt lgkmcnt(0)
	s_add_i32 s30, s30, s25
	s_cmpk_lt_i32 s28, 0xb00
	s_cbranch_scc0 .LBB0_15
.LBB0_21:
	s_mul_hi_i32 s6, s28, 0x2e8ba2e9
	s_lshr_b32 s7, s6, 31
	s_ashr_i32 s6, s6, 5
	s_add_i32 s6, s6, s7
	s_mul_i32 s7, s6, 0xffffea00
	s_add_i32 s31, s29, s7
	s_lshl_b32 s18, s6, 6
	s_and_b32 s7, s31, 0xe0
	s_cmpk_lt_u32 s7, 0x80
	s_mulk_i32 s6, 0xf500
	s_cselect_b64 vcc, -1, 0
	s_add_i32 s6, s30, s6
	v_or_b32_e32 v2, s7, v22
	s_and_b32 s6, s6, 0xffffff80
	v_or_b32_e32 v4, s6, v2
	s_addk_i32 s6, 0xa80
	v_add_u32_e32 v2, s6, v2
	v_cndmask_b32_e32 v2, v2, v4, vcc
	v_mov_b32_e32 v4, v3
	v_mov_b32_e32 v5, v3
	v_cmp_lt_i32_e64 s[6:7], -1, v2
	v_lshl_add_u64 v[18:19], v[2:3], 2, v[8:9]
	v_mov_b32_e32 v2, v3
	v_mov_b64_e32 v[12:13], v[4:5]
	v_or_b32_e32 v20, s18, v15
	v_mov_b64_e32 v[10:11], v[2:3]
	v_mov_b32_e32 v100, 0
	v_mov_b32_e32 v101, 0
	v_mov_b32_e32 v102, 0
	v_mov_b32_e32 v103, 0
	v_mov_b32_e32 v132, 1.0
	s_and_saveexec_b64 s[8:9], s[6:7]
	s_cbranch_execz .LBB0_23
	v_mad_i64_i32 v[4:5], s[20:21], v20, s26, v[18:19]
	global_load_dwordx4 v[100:103], v[4:5], off nt
.LBB0_23:
	s_or_b64 exec, exec, s[8:9]
	s_cmpk_lt_u32 s18, 0x400
	s_cselect_b64 s[8:9], -1, 0
	s_and_b64 s[20:21], s[4:5], s[8:9]
	v_cndmask_b32_e64 v2, 0, 1, s[20:21]
	v_cmp_ne_u32_e64 s[8:9], 1, v2
	s_andn2_b64 vcc, exec, s[20:21]
	s_cbranch_vccnz .LBB0_25
	v_mov_b32_e32 v21, v3
	v_lshl_add_u64 v[4:5], v[20:21], 2, v[6:7]
	global_load_dword v132, v[4:5], off
.LBB0_25:
	v_mov_b32_e32 v4, v3
	v_mov_b32_e32 v5, v3
	v_mov_b32_e32 v2, v3
	v_mov_b64_e32 v[12:13], v[4:5]
	v_mov_b64_e32 v[10:11], v[2:3]
	v_mov_b32_e32 v104, 0
	v_mov_b32_e32 v105, 0
	v_mov_b32_e32 v106, 0
	v_mov_b32_e32 v107, 0
	v_mov_b32_e32 v134, 1.0
	s_and_saveexec_b64 s[20:21], s[6:7]
	s_cbranch_execz .LBB0_27
	v_or_b32_e32 v2, s18, v23
	v_mad_i64_i32 v[4:5], s[34:35], v2, s26, v[18:19]
	global_load_dwordx4 v[104:107], v[4:5], off nt
.LBB0_27:
	s_or_b64 exec, exec, s[20:21]
	s_and_b64 vcc, exec, s[8:9]
	v_add_u32_e32 v20, s18, v15
	s_cbranch_vccnz .LBB0_29
	v_mov_b32_e32 v21, v3
	v_lshl_add_u64 v[4:5], v[20:21], 2, v[6:7]
	global_load_dword v134, v[4:5], off offset:32
.LBB0_29:
	v_add_u32_e32 v2, 0x420, v31
	v_add_u32_e32 v2, 0x428, v31
	v_mov_b32_e32 v4, v3
	v_mov_b32_e32 v5, v3
	v_mov_b32_e32 v2, v3
	v_mov_b64_e32 v[12:13], v[4:5]
	v_mov_b64_e32 v[10:11], v[2:3]
	v_mov_b32_e32 v108, 0
	v_mov_b32_e32 v109, 0
	v_mov_b32_e32 v110, 0
	v_mov_b32_e32 v111, 0
	v_mov_b32_e32 v136, 1.0
	s_and_saveexec_b64 s[20:21], s[6:7]
	s_cbranch_execz .LBB0_31
	v_or_b32_e32 v2, s18, v24
	v_mad_i64_i32 v[4:5], s[34:35], v2, s26, v[18:19]
	global_load_dwordx4 v[108:111], v[4:5], off nt
.LBB0_31:
	s_or_b64 exec, exec, s[20:21]
	s_and_b64 vcc, exec, s[8:9]
	s_cbranch_vccnz .LBB0_33
	v_mov_b32_e32 v21, v3
	v_lshl_add_u64 v[4:5], v[20:21], 2, v[6:7]
	global_load_dword v136, v[4:5], off offset:64
.LBB0_33:
	v_add_u32_e32 v2, 0x840, v31
	v_add_u32_e32 v2, 0x848, v31
	v_mov_b32_e32 v4, v3
	v_mov_b32_e32 v5, v3
	v_mov_b32_e32 v2, v3
	v_mov_b64_e32 v[12:13], v[4:5]
	v_mov_b64_e32 v[10:11], v[2:3]
	v_mov_b32_e32 v112, 0
	v_mov_b32_e32 v113, 0
	v_mov_b32_e32 v114, 0
	v_mov_b32_e32 v115, 0
	v_mov_b32_e32 v138, 1.0
	s_and_saveexec_b64 s[20:21], s[6:7]
	s_cbranch_execz .LBB0_35
	v_or_b32_e32 v2, s18, v25
	v_mad_i64_i32 v[4:5], s[34:35], v2, s26, v[18:19]
	global_load_dwordx4 v[112:115], v[4:5], off nt
.LBB0_35:
	s_or_b64 exec, exec, s[20:21]
	s_and_b64 vcc, exec, s[8:9]
	s_cbranch_vccnz .LBB0_37
	v_mov_b32_e32 v21, v3
	v_lshl_add_u64 v[4:5], v[20:21], 2, v[6:7]
	global_load_dword v138, v[4:5], off offset:96
.LBB0_37:
	v_add_u32_e32 v2, 0xc60, v31
	v_add_u32_e32 v2, 0xc68, v31
	v_mov_b32_e32 v4, v3
	v_mov_b32_e32 v5, v3
	v_mov_b32_e32 v2, v3
	v_mov_b64_e32 v[12:13], v[4:5]
	v_mov_b64_e32 v[10:11], v[2:3]
	v_mov_b32_e32 v116, 0
	v_mov_b32_e32 v117, 0
	v_mov_b32_e32 v118, 0
	v_mov_b32_e32 v119, 0
	v_mov_b32_e32 v140, 1.0
	s_and_saveexec_b64 s[20:21], s[6:7]
	s_cbranch_execz .LBB0_39
	v_or_b32_e32 v2, s18, v26
	v_mad_i64_i32 v[4:5], s[34:35], v2, s26, v[18:19]
	global_load_dwordx4 v[116:119], v[4:5], off nt
.LBB0_39:
	s_or_b64 exec, exec, s[20:21]
	s_and_b64 vcc, exec, s[8:9]
	s_cbranch_vccnz .LBB0_41
	v_mov_b32_e32 v21, v3
	v_lshl_add_u64 v[4:5], v[20:21], 2, v[6:7]
	global_load_dword v140, v[4:5], off offset:128
.LBB0_41:
	v_add_u32_e32 v2, 0x1080, v31
	v_add_u32_e32 v2, 0x1088, v31
	v_mov_b32_e32 v4, v3
	v_mov_b32_e32 v5, v3
	v_mov_b32_e32 v2, v3
	v_mov_b64_e32 v[12:13], v[4:5]
	v_mov_b64_e32 v[10:11], v[2:3]
	v_mov_b32_e32 v120, 0
	v_mov_b32_e32 v121, 0
	v_mov_b32_e32 v122, 0
	v_mov_b32_e32 v123, 0
	v_mov_b32_e32 v142, 1.0
	s_and_saveexec_b64 s[20:21], s[6:7]
	s_cbranch_execz .LBB0_43
	v_or_b32_e32 v2, s18, v27
	v_mad_i64_i32 v[4:5], s[34:35], v2, s26, v[18:19]
	global_load_dwordx4 v[120:123], v[4:5], off nt
.LBB0_43:
	s_or_b64 exec, exec, s[20:21]
	s_and_b64 vcc, exec, s[8:9]
	s_cbranch_vccnz .LBB0_45
	v_mov_b32_e32 v21, v3
	v_lshl_add_u64 v[4:5], v[20:21], 2, v[6:7]
	global_load_dword v142, v[4:5], off offset:160
.LBB0_45:
	v_add_u32_e32 v2, 0x14a0, v31
	v_add_u32_e32 v2, 0x14a8, v31
	v_mov_b32_e32 v4, v3
	v_mov_b32_e32 v5, v3
	v_mov_b32_e32 v2, v3
	v_mov_b64_e32 v[12:13], v[4:5]
	v_mov_b64_e32 v[10:11], v[2:3]
	v_mov_b32_e32 v124, 0
	v_mov_b32_e32 v125, 0
	v_mov_b32_e32 v126, 0
	v_mov_b32_e32 v127, 0
	v_mov_b32_e32 v144, 1.0
	s_and_saveexec_b64 s[20:21], s[6:7]
	s_cbranch_execz .LBB0_47
	v_or_b32_e32 v2, s18, v28
	v_mad_i64_i32 v[4:5], s[34:35], v2, s26, v[18:19]
	global_load_dwordx4 v[124:127], v[4:5], off nt
.LBB0_47:
	s_or_b64 exec, exec, s[20:21]
	s_and_b64 vcc, exec, s[8:9]
	s_cbranch_vccnz .LBB0_49
	v_mov_b32_e32 v21, v3
	v_lshl_add_u64 v[4:5], v[20:21], 2, v[6:7]
	global_load_dword v144, v[4:5], off offset:192
.LBB0_49:
	v_add_u32_e32 v2, 0x18c0, v31
	v_add_u32_e32 v2, 0x18c8, v31
	v_mov_b32_e32 v4, v3
	v_mov_b32_e32 v5, v3
	v_mov_b32_e32 v2, v3
	v_mov_b64_e32 v[12:13], v[4:5]
	v_mov_b64_e32 v[10:11], v[2:3]
	v_mov_b32_e32 v128, 0
	v_mov_b32_e32 v129, 0
	v_mov_b32_e32 v130, 0
	v_mov_b32_e32 v131, 0
	v_mov_b32_e32 v146, 1.0
	s_and_saveexec_b64 s[20:21], s[6:7]
	s_cbranch_execz .LBB0_51
	v_or_b32_e32 v2, s18, v29
	v_mad_i64_i32 v[4:5], s[6:7], v2, s26, v[18:19]
	global_load_dwordx4 v[128:131], v[4:5], off nt
.LBB0_51:
	s_or_b64 exec, exec, s[20:21]
	s_and_b64 vcc, exec, s[8:9]
	s_cbranch_vccnz .LBB0_20
	v_mov_b32_e32 v21, v3
	v_lshl_add_u64 v[4:5], v[20:21], 2, v[6:7]
	global_load_dword v146, v[4:5], off offset:224
	s_branch .LBB0_20

.LBB0_1116:
	s_waitcnt vmcnt(0)
	v_pk_mul_f32 v[100:101], v[100:101], v[132:133] op_sel_hi:[1,0]
	v_pk_mul_f32 v[102:103], v[102:103], v[132:133] op_sel_hi:[1,0]
	v_pk_mul_f32 v[104:105], v[104:105], v[134:135] op_sel_hi:[1,0]
	v_pk_mul_f32 v[106:107], v[106:107], v[134:135] op_sel_hi:[1,0]
	v_pk_mul_f32 v[108:109], v[108:109], v[136:137] op_sel_hi:[1,0]
	v_pk_mul_f32 v[110:111], v[110:111], v[136:137] op_sel_hi:[1,0]
	v_pk_mul_f32 v[112:113], v[112:113], v[138:139] op_sel_hi:[1,0]
	v_pk_mul_f32 v[114:115], v[114:115], v[138:139] op_sel_hi:[1,0]
	v_pk_mul_f32 v[116:117], v[116:117], v[140:141] op_sel_hi:[1,0]
	v_pk_mul_f32 v[118:119], v[118:119], v[140:141] op_sel_hi:[1,0]
	v_pk_mul_f32 v[120:121], v[120:121], v[142:143] op_sel_hi:[1,0]
	v_pk_mul_f32 v[122:123], v[122:123], v[142:143] op_sel_hi:[1,0]
	v_pk_mul_f32 v[124:125], v[124:125], v[144:145] op_sel_hi:[1,0]
	v_pk_mul_f32 v[126:127], v[126:127], v[144:145] op_sel_hi:[1,0]
	v_pk_mul_f32 v[128:129], v[128:129], v[146:147] op_sel_hi:[1,0]
	v_pk_mul_f32 v[130:131], v[130:131], v[146:147] op_sel_hi:[1,0]
	ds_write2_b32 v21, v100, v101 offset1:1
	ds_write2_b32 v21, v102, v103 offset0:2 offset1:3
	v_add_u32_e32 v0, 0x420, v21
	ds_write2_b32 v0, v104, v105 offset1:1
	ds_write2_b32 v0, v106, v107 offset0:2 offset1:3
	v_add_u32_e32 v0, 0x840, v21
	ds_write2_b32 v0, v108, v109 offset1:1
	ds_write2_b32 v0, v110, v111 offset0:2 offset1:3
	v_add_u32_e32 v0, 0xc60, v21
	ds_write2_b32 v0, v112, v113 offset1:1
	ds_write2_b32 v0, v114, v115 offset0:2 offset1:3
	v_add_u32_e32 v0, 0x1080, v21
	ds_write2_b32 v0, v116, v117 offset1:1
	ds_write2_b32 v0, v118, v119 offset0:2 offset1:3
	v_add_u32_e32 v0, 0x14a0, v21
	ds_write2_b32 v0, v120, v121 offset1:1
	ds_write2_b32 v0, v122, v123 offset0:2 offset1:3
	v_add_u32_e32 v0, 0x18c0, v21
	ds_write2_b32 v0, v124, v125 offset1:1
	ds_write2_b32 v0, v126, v127 offset0:2 offset1:3
	v_add_u32_e32 v0, 0x1ce0, v21
	ds_write2_b32 v0, v128, v129 offset1:1
	ds_write2_b32 v0, v130, v131 offset0:2 offset1:3
	s_waitcnt lgkmcnt(0)
	ds_read2_b32 v[12:13], v20 offset0:33 offset1:41
	ds_read2_b32 v[22:23], v20 offset1:8
	v_add_u32_e32 v0, s52, v15
	ds_read2_b32 v[24:25], v20 offset0:66 offset1:74
	ds_read2_b32 v[26:27], v20 offset0:99 offset1:107
	ds_read2_b32 v[28:29], v20 offset0:132 offset1:140
	ds_read2_b32 v[30:31], v20 offset0:165 offset1:173
	ds_read2_b32 v[32:33], v20 offset0:198 offset1:206
	ds_read2_b32 v[34:35], v20 offset0:231 offset1:239
	v_ashrrev_i32_e32 v7, 31, v0
	s_waitcnt lgkmcnt(6)
	v_cvt_pk_bf16_f32 v2, v22, v12
	v_mul_lo_u32 v7, s20, v7
	v_mul_lo_u32 v12, s21, v0
	v_mad_u64_u32 v[36:37], s[4:5], s20, v0, 0
	s_ashr_i32 s23, s22, 31
	v_add3_u32 v37, v37, v7, v12
	v_lshl_add_u64 v[36:37], v[36:37], 1, s[16:17]
	s_lshl_b64 s[4:5], s[22:23], 1
	v_lshl_add_u64 v[36:37], v[36:37], 0, s[4:5]
	v_mov_b32_e32 v7, v1
	s_waitcnt lgkmcnt(4)
	v_cvt_pk_bf16_f32 v3, v24, v26
	s_waitcnt lgkmcnt(2)
	v_cvt_pk_bf16_f32 v4, v28, v30
	s_waitcnt lgkmcnt(0)
	v_cvt_pk_bf16_f32 v5, v32, v34
	v_lshl_add_u64 v[36:37], v[36:37], 0, v[6:7]
	v_add_u32_e32 v12, 8, v0
	global_store_dwordx4 v[36:37], v[2:5], off
	s_add_i32 s40, s40, s26
	s_add_i32 s47, s47, s48
	v_cvt_pk_bf16_f32 v2, v23, v13
	v_ashrrev_i32_e32 v13, 31, v12
	v_mul_lo_u32 v22, s20, v13
	v_mul_lo_u32 v23, s21, v12
	v_mad_u64_u32 v[12:13], s[6:7], s20, v12, 0
	v_add3_u32 v13, v13, v22, v23
	v_lshl_add_u64 v[12:13], v[12:13], 1, s[16:17]
	v_lshl_add_u64 v[12:13], v[12:13], 0, s[4:5]
	v_cvt_pk_bf16_f32 v3, v25, v27
	v_cvt_pk_bf16_f32 v4, v29, v31
	v_cvt_pk_bf16_f32 v5, v33, v35
	v_lshl_add_u64 v[12:13], v[12:13], 0, v[6:7]
	global_store_dwordx4 v[12:13], v[2:5], off
	ds_read2_b32 v[12:13], v20 offset0:16 offset1:24
	ds_read2_b32 v[22:23], v20 offset0:49 offset1:57
	ds_read2_b32 v[24:25], v20 offset0:82 offset1:90
	ds_read2_b32 v[26:27], v20 offset0:115 offset1:123
	ds_read2_b32 v[28:29], v20 offset0:148 offset1:156
	ds_read2_b32 v[30:31], v20 offset0:181 offset1:189
	ds_read2_b32 v[32:33], v20 offset0:214 offset1:222
	ds_read2_b32 v[34:35], v20 offset0:247 offset1:255
	s_add_i32 s50, s50, s51
	s_waitcnt lgkmcnt(6)
	v_cvt_pk_bf16_f32 v2, v12, v22
	v_add_u32_e32 v12, 16, v0
	v_ashrrev_i32_e32 v22, 31, v12
	s_waitcnt lgkmcnt(4)
	v_cvt_pk_bf16_f32 v3, v24, v26
	v_mul_lo_u32 v22, s20, v22
	v_mul_lo_u32 v24, s21, v12
	v_mad_u64_u32 v[36:37], s[6:7], s20, v12, 0
	v_add3_u32 v37, v37, v22, v24
	v_lshl_add_u64 v[36:37], v[36:37], 1, s[16:17]
	v_lshl_add_u64 v[36:37], v[36:37], 0, s[4:5]
	v_add_u32_e32 v0, 24, v0
	s_waitcnt lgkmcnt(2)
	v_cvt_pk_bf16_f32 v4, v28, v30
	s_waitcnt lgkmcnt(0)
	v_cvt_pk_bf16_f32 v5, v32, v34
	v_lshl_add_u64 v[36:37], v[36:37], 0, v[6:7]
	v_ashrrev_i32_e32 v12, 31, v0
	global_store_dwordx4 v[36:37], v[2:5], off
	v_mul_lo_u32 v22, s20, v12
	s_cmp_lt_i32 s40, s39
	v_cvt_pk_bf16_f32 v2, v13, v23
	v_mul_lo_u32 v23, s21, v0
	v_mad_u64_u32 v[12:13], s[6:7], s20, v0, 0
	v_add3_u32 v13, v13, v22, v23
	v_lshl_add_u64 v[12:13], v[12:13], 1, s[16:17]
	v_lshl_add_u64 v[12:13], v[12:13], 0, s[4:5]
	v_cvt_pk_bf16_f32 v3, v25, v27
	v_cvt_pk_bf16_f32 v4, v29, v31
	v_cvt_pk_bf16_f32 v5, v33, v35
	v_lshl_add_u64 v[12:13], v[12:13], 0, v[6:7]
	global_store_dwordx4 v[12:13], v[2:5], off
	s_waitcnt lgkmcnt(0)
	s_cbranch_scc0 .LBB0_1092

.LBB0_1140:
	v_mov_b32_e32 v2, v1
	v_mov_b32_e32 v3, v1
	s_lshl_b32 s22, s8, 6
	v_cmp_lt_i32_e64 s[4:5], -1, v0
	v_lshl_add_u64 v[12:13], v[0:1], 2, v[8:9]
	v_mov_b32_e32 v0, v1
	v_mov_b64_e32 v[4:5], v[2:3]
	v_add_u32_e32 v7, s22, v15
	v_mov_b64_e32 v[2:3], v[0:1]
	v_mov_b32_e32 v100, 0
	v_mov_b32_e32 v101, 0
	v_mov_b32_e32 v102, 0
	v_mov_b32_e32 v103, 0
	v_mov_b32_e32 v132, 1.0
	s_and_saveexec_b64 s[6:7], s[4:5]
	s_cbranch_execz .LBB0_1142
	v_ashrrev_i32_e32 v0, 31, v7
	v_mul_lo_u32 v4, s19, v7
	v_mul_lo_u32 v0, s18, v0
	v_mad_u64_u32 v[2:3], s[8:9], s18, v7, 0
	v_add3_u32 v3, v3, v0, v4
	v_lshl_add_u64 v[2:3], v[2:3], 2, v[12:13]
	global_load_dwordx4 v[100:103], v[2:3], off nt
.LBB0_1142:
	s_or_b64 exec, exec, s[6:7]
	v_cndmask_b32_e64 v0, 0, 1, s[0:1]
	v_cmp_ne_u32_e64 s[6:7], 1, v0
	s_andn2_b64 vcc, exec, s[0:1]
	s_cbranch_vccnz .LBB0_1146
	v_cmp_le_i32_e32 vcc, s44, v7
	v_cmp_gt_i32_e64 s[8:9], s42, v7
	s_and_b64 s[54:55], vcc, s[8:9]
	s_and_saveexec_b64 s[8:9], s[54:55]
	s_cbranch_execz .LBB0_1145
	v_subrev_u32_e32 v0, s44, v7
	v_lshl_add_u64 v[22:23], v[0:1], 2, v[10:11]
	global_load_dword v132, v[22:23], off

.LBB0_1146:
	v_mov_b32_e32 v2, v1
	v_mov_b32_e32 v3, v1
	v_mov_b32_e32 v0, v1
	v_mov_b64_e32 v[4:5], v[2:3]
	v_add_u32_e32 v22, s22, v17
	v_mov_b64_e32 v[2:3], v[0:1]
	v_mov_b32_e32 v104, 0
	v_mov_b32_e32 v105, 0
	v_mov_b32_e32 v106, 0
	v_mov_b32_e32 v107, 0
	v_mov_b32_e32 v134, 1.0
	s_and_saveexec_b64 s[8:9], s[4:5]
	s_cbranch_execz .LBB0_1148
	v_ashrrev_i32_e32 v0, 31, v22
	v_mul_lo_u32 v4, s19, v22
	v_mul_lo_u32 v0, s18, v0
	v_mad_u64_u32 v[2:3], s[54:55], s18, v22, 0
	v_add3_u32 v3, v3, v0, v4
	v_lshl_add_u64 v[2:3], v[2:3], 2, v[12:13]
	global_load_dwordx4 v[104:107], v[2:3], off nt
.LBB0_1148:
	s_or_b64 exec, exec, s[8:9]
	s_and_b64 vcc, exec, s[6:7]
	s_cbranch_vccnz .LBB0_1152
	v_cmp_le_i32_e32 vcc, s44, v22
	v_cmp_gt_i32_e64 s[8:9], s42, v22
	s_and_b64 s[54:55], vcc, s[8:9]
	s_and_saveexec_b64 s[8:9], s[54:55]
	s_cbranch_execz .LBB0_1151
	v_subrev_u32_e32 v0, s44, v22
	v_lshl_add_u64 v[22:23], v[0:1], 2, v[10:11]
	global_load_dword v134, v[22:23], off

.LBB0_1152:
	v_add_u32_e32 v0, 0x420, v21
	v_add_u32_e32 v0, 0x428, v21
	v_mov_b32_e32 v2, v1
	v_mov_b32_e32 v3, v1
	v_mov_b32_e32 v0, v1
	v_mov_b64_e32 v[4:5], v[2:3]
	v_add_u32_e32 v22, s22, v18
	v_mov_b64_e32 v[2:3], v[0:1]
	v_mov_b32_e32 v108, 0
	v_mov_b32_e32 v109, 0
	v_mov_b32_e32 v110, 0
	v_mov_b32_e32 v111, 0
	v_mov_b32_e32 v136, 1.0
	s_and_saveexec_b64 s[8:9], s[4:5]
	s_cbranch_execz .LBB0_1154
	v_ashrrev_i32_e32 v0, 31, v22
	v_mul_lo_u32 v4, s19, v22
	v_mul_lo_u32 v0, s18, v0
	v_mad_u64_u32 v[2:3], s[54:55], s18, v22, 0
	v_add3_u32 v3, v3, v0, v4
	v_lshl_add_u64 v[2:3], v[2:3], 2, v[12:13]
	global_load_dwordx4 v[108:111], v[2:3], off nt
.LBB0_1154:
	s_or_b64 exec, exec, s[8:9]
	s_and_b64 vcc, exec, s[6:7]
	s_cbranch_vccnz .LBB0_1158
	v_cmp_le_i32_e32 vcc, s44, v22
	v_cmp_gt_i32_e64 s[8:9], s42, v22
	s_and_b64 s[54:55], vcc, s[8:9]
	s_and_saveexec_b64 s[8:9], s[54:55]
	s_cbranch_execz .LBB0_1157
	v_subrev_u32_e32 v0, s44, v22
	v_lshl_add_u64 v[22:23], v[0:1], 2, v[10:11]
	global_load_dword v136, v[22:23], off

.LBB0_1158:
	v_add_u32_e32 v0, 0x840, v21
	v_add_u32_e32 v0, 0x848, v21
	v_mov_b32_e32 v2, v1
	v_mov_b32_e32 v3, v1
	v_mov_b32_e32 v0, v1
	v_mov_b64_e32 v[4:5], v[2:3]
	v_add_u32_e32 v22, s22, v19
	v_mov_b64_e32 v[2:3], v[0:1]
	v_mov_b32_e32 v112, 0
	v_mov_b32_e32 v113, 0
	v_mov_b32_e32 v114, 0
	v_mov_b32_e32 v115, 0
	v_mov_b32_e32 v138, 1.0
	s_and_saveexec_b64 s[8:9], s[4:5]
	s_cbranch_execz .LBB0_1160
	v_ashrrev_i32_e32 v0, 31, v22
	v_mul_lo_u32 v4, s19, v22
	v_mul_lo_u32 v0, s18, v0
	v_mad_u64_u32 v[2:3], s[54:55], s18, v22, 0
	v_add3_u32 v3, v3, v0, v4
	v_lshl_add_u64 v[2:3], v[2:3], 2, v[12:13]
	global_load_dwordx4 v[112:115], v[2:3], off nt
.LBB0_1160:
	s_or_b64 exec, exec, s[8:9]
	s_and_b64 vcc, exec, s[6:7]
	s_cbranch_vccnz .LBB0_1164
	v_cmp_le_i32_e32 vcc, s44, v22
	v_cmp_gt_i32_e64 s[8:9], s42, v22
	s_and_b64 s[54:55], vcc, s[8:9]
	s_and_saveexec_b64 s[8:9], s[54:55]
	s_cbranch_execz .LBB0_1163
	v_subrev_u32_e32 v0, s44, v22
	v_lshl_add_u64 v[22:23], v[0:1], 2, v[10:11]
	global_load_dword v138, v[22:23], off

.LBB0_1164:
	v_add_u32_e32 v0, 0xc60, v21
	v_add_u32_e32 v0, 0xc68, v21
	v_mov_b32_e32 v2, v1
	v_mov_b32_e32 v3, v1
	v_mov_b32_e32 v0, v1
	v_mov_b64_e32 v[4:5], v[2:3]
	v_add_u32_e32 v22, 32, v7
	v_mov_b64_e32 v[2:3], v[0:1]
	v_mov_b32_e32 v116, 0
	v_mov_b32_e32 v117, 0
	v_mov_b32_e32 v118, 0
	v_mov_b32_e32 v119, 0
	v_mov_b32_e32 v140, 1.0
	s_and_saveexec_b64 s[8:9], s[4:5]
	s_cbranch_execz .LBB0_1166
	v_ashrrev_i32_e32 v0, 31, v22
	v_mul_lo_u32 v4, s19, v22
	v_mul_lo_u32 v0, s18, v0
	v_mad_u64_u32 v[2:3], s[54:55], s18, v22, 0
	v_add3_u32 v3, v3, v0, v4
	v_lshl_add_u64 v[2:3], v[2:3], 2, v[12:13]
	global_load_dwordx4 v[116:119], v[2:3], off nt
.LBB0_1166:
	s_or_b64 exec, exec, s[8:9]
	s_and_b64 vcc, exec, s[6:7]
	s_cbranch_vccnz .LBB0_1170
	v_cmp_le_i32_e32 vcc, s44, v22
	v_cmp_gt_i32_e64 s[8:9], s42, v22
	s_and_b64 s[54:55], vcc, s[8:9]
	s_and_saveexec_b64 s[8:9], s[54:55]
	s_cbranch_execz .LBB0_1169
	v_subrev_u32_e32 v0, s44, v22
	v_lshl_add_u64 v[22:23], v[0:1], 2, v[10:11]
	global_load_dword v140, v[22:23], off

.LBB0_1170:
	v_add_u32_e32 v0, 0x1080, v21
	v_add_u32_e32 v0, 0x1088, v21
	v_mov_b32_e32 v2, v1
	v_mov_b32_e32 v3, v1
	v_mov_b32_e32 v0, v1
	v_mov_b64_e32 v[4:5], v[2:3]
	v_add_u32_e32 v22, 40, v7
	v_mov_b64_e32 v[2:3], v[0:1]
	v_mov_b32_e32 v120, 0
	v_mov_b32_e32 v121, 0
	v_mov_b32_e32 v122, 0
	v_mov_b32_e32 v123, 0
	v_mov_b32_e32 v142, 1.0
	s_and_saveexec_b64 s[8:9], s[4:5]
	s_cbranch_execz .LBB0_1172
	v_ashrrev_i32_e32 v0, 31, v22
	v_mul_lo_u32 v4, s19, v22
	v_mul_lo_u32 v0, s18, v0
	v_mad_u64_u32 v[2:3], s[54:55], s18, v22, 0
	v_add3_u32 v3, v3, v0, v4
	v_lshl_add_u64 v[2:3], v[2:3], 2, v[12:13]
	global_load_dwordx4 v[120:123], v[2:3], off nt
.LBB0_1172:
	s_or_b64 exec, exec, s[8:9]
	s_and_b64 vcc, exec, s[6:7]
	s_cbranch_vccnz .LBB0_1176
	v_cmp_le_i32_e32 vcc, s44, v22
	v_cmp_gt_i32_e64 s[8:9], s42, v22
	s_and_b64 s[54:55], vcc, s[8:9]
	s_and_saveexec_b64 s[8:9], s[54:55]
	s_cbranch_execz .LBB0_1175
	v_subrev_u32_e32 v0, s44, v22
	v_lshl_add_u64 v[22:23], v[0:1], 2, v[10:11]
	global_load_dword v142, v[22:23], off

.LBB0_1176:
	v_add_u32_e32 v0, 0x14a0, v21
	v_add_u32_e32 v0, 0x14a8, v21
	v_mov_b32_e32 v2, v1
	v_mov_b32_e32 v3, v1
	v_mov_b32_e32 v0, v1
	v_mov_b64_e32 v[4:5], v[2:3]
	v_add_u32_e32 v22, 48, v7
	v_mov_b64_e32 v[2:3], v[0:1]
	v_mov_b32_e32 v124, 0
	v_mov_b32_e32 v125, 0
	v_mov_b32_e32 v126, 0
	v_mov_b32_e32 v127, 0
	v_mov_b32_e32 v144, 1.0
	s_and_saveexec_b64 s[8:9], s[4:5]
	s_cbranch_execz .LBB0_1178
	v_ashrrev_i32_e32 v0, 31, v22
	v_mul_lo_u32 v4, s19, v22
	v_mul_lo_u32 v0, s18, v0
	v_mad_u64_u32 v[2:3], s[54:55], s18, v22, 0
	v_add3_u32 v3, v3, v0, v4
	v_lshl_add_u64 v[2:3], v[2:3], 2, v[12:13]
	global_load_dwordx4 v[124:127], v[2:3], off nt
.LBB0_1178:
	s_or_b64 exec, exec, s[8:9]
	s_and_b64 vcc, exec, s[6:7]
	s_cbranch_vccnz .LBB0_1182
	v_cmp_le_i32_e32 vcc, s44, v22
	v_cmp_gt_i32_e64 s[8:9], s42, v22
	s_and_b64 s[54:55], vcc, s[8:9]
	s_and_saveexec_b64 s[8:9], s[54:55]
	s_cbranch_execz .LBB0_1181
	v_subrev_u32_e32 v0, s44, v22
	v_lshl_add_u64 v[22:23], v[0:1], 2, v[10:11]
	global_load_dword v144, v[22:23], off

.LBB0_1182:
	v_add_u32_e32 v0, 0x18c0, v21
	v_add_u32_e32 v0, 0x18c8, v21
	v_mov_b32_e32 v2, v1
	v_mov_b32_e32 v3, v1
	v_mov_b32_e32 v0, v1
	v_mov_b64_e32 v[4:5], v[2:3]
	v_add_u32_e32 v7, 56, v7
	v_mov_b64_e32 v[2:3], v[0:1]
	v_mov_b32_e32 v128, 0
	v_mov_b32_e32 v129, 0
	v_mov_b32_e32 v130, 0
	v_mov_b32_e32 v131, 0
	v_mov_b32_e32 v146, 1.0
	s_and_saveexec_b64 s[8:9], s[4:5]
	s_cbranch_execz .LBB0_1184
	v_ashrrev_i32_e32 v0, 31, v7
	v_mul_lo_u32 v4, s19, v7
	v_mul_lo_u32 v0, s18, v0
	v_mad_u64_u32 v[2:3], s[4:5], s18, v7, 0
	v_add3_u32 v3, v3, v0, v4
	v_lshl_add_u64 v[2:3], v[2:3], 2, v[12:13]
	global_load_dwordx4 v[128:131], v[2:3], off nt
.LBB0_1184:
	s_or_b64 exec, exec, s[8:9]
	s_and_b64 vcc, exec, s[6:7]
	s_cbranch_vccnz .LBB0_1116
	v_cmp_le_i32_e32 vcc, s44, v7
	v_cmp_gt_i32_e64 s[4:5], s42, v7
	s_and_b64 s[6:7], vcc, s[4:5]
	s_and_saveexec_b64 s[4:5], s[6:7]
	s_cbranch_execz .LBB0_1115
	v_subrev_u32_e32 v0, s44, v7
	v_lshl_add_u64 v[12:13], v[0:1], 2, v[10:11]
	global_load_dword v146, v[12:13], off
	s_branch .LBB0_1115

.LBB0_1224:
	s_waitcnt vmcnt(0)
	v_pk_mul_f32 v[100:101], v[100:101], v[132:133] op_sel_hi:[1,0]
	v_pk_mul_f32 v[102:103], v[102:103], v[132:133] op_sel_hi:[1,0]
	v_pk_mul_f32 v[104:105], v[104:105], v[134:135] op_sel_hi:[1,0]
	v_pk_mul_f32 v[106:107], v[106:107], v[134:135] op_sel_hi:[1,0]
	v_pk_mul_f32 v[108:109], v[108:109], v[136:137] op_sel_hi:[1,0]
	v_pk_mul_f32 v[110:111], v[110:111], v[136:137] op_sel_hi:[1,0]
	v_pk_mul_f32 v[112:113], v[112:113], v[138:139] op_sel_hi:[1,0]
	v_pk_mul_f32 v[114:115], v[114:115], v[138:139] op_sel_hi:[1,0]
	v_pk_mul_f32 v[116:117], v[116:117], v[140:141] op_sel_hi:[1,0]
	v_pk_mul_f32 v[118:119], v[118:119], v[140:141] op_sel_hi:[1,0]
	v_pk_mul_f32 v[120:121], v[120:121], v[142:143] op_sel_hi:[1,0]
	v_pk_mul_f32 v[122:123], v[122:123], v[142:143] op_sel_hi:[1,0]
	v_pk_mul_f32 v[124:125], v[124:125], v[144:145] op_sel_hi:[1,0]
	v_pk_mul_f32 v[126:127], v[126:127], v[144:145] op_sel_hi:[1,0]
	v_pk_mul_f32 v[128:129], v[128:129], v[146:147] op_sel_hi:[1,0]
	v_pk_mul_f32 v[130:131], v[130:131], v[146:147] op_sel_hi:[1,0]
	ds_write2_b32 v20, v100, v101 offset1:1
	ds_write2_b32 v20, v102, v103 offset0:2 offset1:3
	v_add_u32_e32 v0, 0x420, v20
	ds_write2_b32 v0, v104, v105 offset1:1
	ds_write2_b32 v0, v106, v107 offset0:2 offset1:3
	v_add_u32_e32 v0, 0x840, v20
	ds_write2_b32 v0, v108, v109 offset1:1
	ds_write2_b32 v0, v110, v111 offset0:2 offset1:3
	v_add_u32_e32 v0, 0xc60, v20
	ds_write2_b32 v0, v112, v113 offset1:1
	ds_write2_b32 v0, v114, v115 offset0:2 offset1:3
	v_add_u32_e32 v0, 0x1080, v20
	ds_write2_b32 v0, v116, v117 offset1:1
	ds_write2_b32 v0, v118, v119 offset0:2 offset1:3
	v_add_u32_e32 v0, 0x14a0, v20
	ds_write2_b32 v0, v120, v121 offset1:1
	ds_write2_b32 v0, v122, v123 offset0:2 offset1:3
	v_add_u32_e32 v0, 0x18c0, v20
	ds_write2_b32 v0, v124, v125 offset1:1
	ds_write2_b32 v0, v126, v127 offset0:2 offset1:3
	v_add_u32_e32 v0, 0x1ce0, v20
	ds_write2_b32 v0, v128, v129 offset1:1
	ds_write2_b32 v0, v130, v131 offset0:2 offset1:3
	s_waitcnt lgkmcnt(0)
	ds_read2_b32 v[12:13], v19 offset0:33 offset1:41
	ds_read2_b32 v[22:23], v19 offset1:8
	v_add_u32_e32 v0, s52, v14
	ds_read2_b32 v[24:25], v19 offset0:66 offset1:74
	ds_read2_b32 v[26:27], v19 offset0:99 offset1:107
	ds_read2_b32 v[28:29], v19 offset0:132 offset1:140
	ds_read2_b32 v[30:31], v19 offset0:165 offset1:173
	ds_read2_b32 v[32:33], v19 offset0:198 offset1:206
	ds_read2_b32 v[34:35], v19 offset0:231 offset1:239
	v_ashrrev_i32_e32 v7, 31, v0
	s_waitcnt lgkmcnt(6)
	v_cvt_pk_bf16_f32 v2, v22, v12
	v_mul_lo_u32 v7, s20, v7
	v_mul_lo_u32 v12, s21, v0
	v_mad_u64_u32 v[36:37], s[4:5], s20, v0, 0
	s_ashr_i32 s23, s22, 31
	v_add3_u32 v37, v37, v7, v12
	v_lshl_add_u64 v[36:37], v[36:37], 1, s[16:17]
	s_lshl_b64 s[4:5], s[22:23], 1
	v_lshl_add_u64 v[36:37], v[36:37], 0, s[4:5]
	v_mov_b32_e32 v7, v1
	s_waitcnt lgkmcnt(4)
	v_cvt_pk_bf16_f32 v3, v24, v26
	s_waitcnt lgkmcnt(2)
	v_cvt_pk_bf16_f32 v4, v28, v30
	s_waitcnt lgkmcnt(0)
	v_cvt_pk_bf16_f32 v5, v32, v34
	v_lshl_add_u64 v[36:37], v[36:37], 0, v[6:7]
	v_add_u32_e32 v12, 8, v0
	global_store_dwordx4 v[36:37], v[2:5], off
	v_mul_lo_u32 v22, s21, v12
	s_add_i32 s40, s40, s26
	v_cvt_pk_bf16_f32 v2, v23, v13
	v_ashrrev_i32_e32 v13, 31, v12
	v_mul_lo_u32 v21, s20, v13
	v_mad_u64_u32 v[12:13], s[6:7], s20, v12, 0
	v_add3_u32 v13, v13, v21, v22
	v_lshl_add_u64 v[12:13], v[12:13], 1, s[16:17]
	v_lshl_add_u64 v[12:13], v[12:13], 0, s[4:5]
	v_cvt_pk_bf16_f32 v3, v25, v27
	v_cvt_pk_bf16_f32 v4, v29, v31
	v_cvt_pk_bf16_f32 v5, v33, v35
	v_lshl_add_u64 v[12:13], v[12:13], 0, v[6:7]
	global_store_dwordx4 v[12:13], v[2:5], off
	ds_read2_b32 v[12:13], v19 offset0:16 offset1:24
	ds_read2_b32 v[22:23], v19 offset0:49 offset1:57
	ds_read2_b32 v[24:25], v19 offset0:82 offset1:90
	ds_read2_b32 v[26:27], v19 offset0:115 offset1:123
	ds_read2_b32 v[28:29], v19 offset0:148 offset1:156
	ds_read2_b32 v[30:31], v19 offset0:181 offset1:189
	ds_read2_b32 v[32:33], v19 offset0:214 offset1:222
	ds_read2_b32 v[34:35], v19 offset0:247 offset1:255
	s_add_i32 s47, s47, s48
	s_waitcnt lgkmcnt(6)
	v_cvt_pk_bf16_f32 v2, v12, v22
	v_add_u32_e32 v12, 16, v0
	v_ashrrev_i32_e32 v21, 31, v12
	v_mul_lo_u32 v21, s20, v21
	v_mul_lo_u32 v22, s21, v12
	v_mad_u64_u32 v[36:37], s[6:7], s20, v12, 0
	v_add3_u32 v37, v37, v21, v22
	v_lshl_add_u64 v[36:37], v[36:37], 1, s[16:17]
	v_lshl_add_u64 v[36:37], v[36:37], 0, s[4:5]
	v_add_u32_e32 v0, 24, v0
	s_waitcnt lgkmcnt(4)
	v_cvt_pk_bf16_f32 v3, v24, v26
	s_waitcnt lgkmcnt(2)
	v_cvt_pk_bf16_f32 v4, v28, v30
	s_waitcnt lgkmcnt(0)
	v_cvt_pk_bf16_f32 v5, v32, v34
	v_lshl_add_u64 v[36:37], v[36:37], 0, v[6:7]
	v_ashrrev_i32_e32 v12, 31, v0
	global_store_dwordx4 v[36:37], v[2:5], off
	v_mul_lo_u32 v21, s20, v12
	v_mul_lo_u32 v22, s21, v0
	v_cvt_pk_bf16_f32 v2, v13, v23
	v_mad_u64_u32 v[12:13], s[6:7], s20, v0, 0
	v_add3_u32 v13, v13, v21, v22
	v_lshl_add_u64 v[12:13], v[12:13], 1, s[16:17]
	v_lshl_add_u64 v[12:13], v[12:13], 0, s[4:5]
	v_cvt_pk_bf16_f32 v3, v25, v27
	v_cvt_pk_bf16_f32 v4, v29, v31
	v_cvt_pk_bf16_f32 v5, v33, v35
	v_lshl_add_u64 v[12:13], v[12:13], 0, v[6:7]
	global_store_dwordx4 v[12:13], v[2:5], off
	s_waitcnt lgkmcnt(0)
	s_add_i32 s50, s50, s51
	s_cmp_lt_i32 s40, s39
	s_cbranch_scc0 .LBB0_1200

.LBB0_1248:
	v_mov_b32_e32 v2, v1
	v_mov_b32_e32 v3, v1
	s_lshl_b32 s22, s8, 6
	v_cmp_lt_i32_e64 s[4:5], -1, v0
	v_lshl_add_u64 v[12:13], v[0:1], 2, v[8:9]
	v_mov_b32_e32 v0, v1
	v_mov_b64_e32 v[4:5], v[2:3]
	v_add_u32_e32 v7, s22, v14
	v_mov_b64_e32 v[2:3], v[0:1]
	v_mov_b32_e32 v100, 0
	v_mov_b32_e32 v101, 0
	v_mov_b32_e32 v102, 0
	v_mov_b32_e32 v103, 0
	v_mov_b32_e32 v132, 1.0
	s_and_saveexec_b64 s[6:7], s[4:5]
	s_cbranch_execz .LBB0_1250
	v_ashrrev_i32_e32 v0, 31, v7
	v_mul_lo_u32 v4, s19, v7
	v_mul_lo_u32 v0, s18, v0
	v_mad_u64_u32 v[2:3], s[8:9], s18, v7, 0
	v_add3_u32 v3, v3, v0, v4
	v_lshl_add_u64 v[2:3], v[2:3], 2, v[12:13]
	global_load_dwordx4 v[100:103], v[2:3], off nt

.LBB0_1254:
	v_mov_b32_e32 v2, v1
	v_mov_b32_e32 v3, v1
	v_mov_b32_e32 v0, v1
	v_mov_b64_e32 v[4:5], v[2:3]
	v_add_u32_e32 v21, s22, v16
	v_mov_b64_e32 v[2:3], v[0:1]
	v_mov_b32_e32 v104, 0
	v_mov_b32_e32 v105, 0
	v_mov_b32_e32 v106, 0
	v_mov_b32_e32 v107, 0
	v_mov_b32_e32 v134, 1.0
	s_and_saveexec_b64 s[8:9], s[4:5]
	s_cbranch_execz .LBB0_1256
	v_ashrrev_i32_e32 v0, 31, v21
	v_mul_lo_u32 v4, s19, v21
	v_mul_lo_u32 v0, s18, v0
	v_mad_u64_u32 v[2:3], s[54:55], s18, v21, 0
	v_add3_u32 v3, v3, v0, v4
	v_lshl_add_u64 v[2:3], v[2:3], 2, v[12:13]
	global_load_dwordx4 v[104:107], v[2:3], off nt
.LBB0_1256:
	s_or_b64 exec, exec, s[8:9]
	s_and_b64 vcc, exec, s[6:7]
	s_cbranch_vccnz .LBB0_1260
	v_cmp_le_i32_e32 vcc, s44, v21
	v_cmp_gt_i32_e64 s[8:9], s42, v21
	s_and_b64 s[54:55], vcc, s[8:9]
	s_and_saveexec_b64 s[8:9], s[54:55]
	s_cbranch_execz .LBB0_1259
	v_subrev_u32_e32 v0, s44, v21
	v_lshl_add_u64 v[22:23], v[0:1], 2, v[10:11]
	global_load_dword v134, v[22:23], off

.LBB0_1260:
	v_add_u32_e32 v0, 0x420, v20
	v_add_u32_e32 v0, 0x428, v20
	v_mov_b32_e32 v2, v1
	v_mov_b32_e32 v3, v1
	v_mov_b32_e32 v0, v1
	v_mov_b64_e32 v[4:5], v[2:3]
	v_add_u32_e32 v21, s22, v17
	v_mov_b64_e32 v[2:3], v[0:1]
	v_mov_b32_e32 v108, 0
	v_mov_b32_e32 v109, 0
	v_mov_b32_e32 v110, 0
	v_mov_b32_e32 v111, 0
	v_mov_b32_e32 v136, 1.0
	s_and_saveexec_b64 s[8:9], s[4:5]
	s_cbranch_execz .LBB0_1262
	v_ashrrev_i32_e32 v0, 31, v21
	v_mul_lo_u32 v4, s19, v21
	v_mul_lo_u32 v0, s18, v0
	v_mad_u64_u32 v[2:3], s[54:55], s18, v21, 0
	v_add3_u32 v3, v3, v0, v4
	v_lshl_add_u64 v[2:3], v[2:3], 2, v[12:13]
	global_load_dwordx4 v[108:111], v[2:3], off nt
.LBB0_1262:
	s_or_b64 exec, exec, s[8:9]
	s_and_b64 vcc, exec, s[6:7]
	s_cbranch_vccnz .LBB0_1266
	v_cmp_le_i32_e32 vcc, s44, v21
	v_cmp_gt_i32_e64 s[8:9], s42, v21
	s_and_b64 s[54:55], vcc, s[8:9]
	s_and_saveexec_b64 s[8:9], s[54:55]
	s_cbranch_execz .LBB0_1265
	v_subrev_u32_e32 v0, s44, v21
	v_lshl_add_u64 v[22:23], v[0:1], 2, v[10:11]
	global_load_dword v136, v[22:23], off

.LBB0_1266:
	v_add_u32_e32 v0, 0x840, v20
	v_add_u32_e32 v0, 0x848, v20
	v_mov_b32_e32 v2, v1
	v_mov_b32_e32 v3, v1
	v_mov_b32_e32 v0, v1
	v_mov_b64_e32 v[4:5], v[2:3]
	v_add_u32_e32 v21, s22, v18
	v_mov_b64_e32 v[2:3], v[0:1]
	v_mov_b32_e32 v112, 0
	v_mov_b32_e32 v113, 0
	v_mov_b32_e32 v114, 0
	v_mov_b32_e32 v115, 0
	v_mov_b32_e32 v138, 1.0
	s_and_saveexec_b64 s[8:9], s[4:5]
	s_cbranch_execz .LBB0_1268
	v_ashrrev_i32_e32 v0, 31, v21
	v_mul_lo_u32 v4, s19, v21
	v_mul_lo_u32 v0, s18, v0
	v_mad_u64_u32 v[2:3], s[54:55], s18, v21, 0
	v_add3_u32 v3, v3, v0, v4
	v_lshl_add_u64 v[2:3], v[2:3], 2, v[12:13]
	global_load_dwordx4 v[112:115], v[2:3], off nt
.LBB0_1268:
	s_or_b64 exec, exec, s[8:9]
	s_and_b64 vcc, exec, s[6:7]
	s_cbranch_vccnz .LBB0_1272
	v_cmp_le_i32_e32 vcc, s44, v21
	v_cmp_gt_i32_e64 s[8:9], s42, v21
	s_and_b64 s[54:55], vcc, s[8:9]
	s_and_saveexec_b64 s[8:9], s[54:55]
	s_cbranch_execz .LBB0_1271
	v_subrev_u32_e32 v0, s44, v21
	v_lshl_add_u64 v[22:23], v[0:1], 2, v[10:11]
	global_load_dword v138, v[22:23], off

.LBB0_1272:
	v_add_u32_e32 v0, 0xc60, v20
	v_add_u32_e32 v0, 0xc68, v20
	v_mov_b32_e32 v2, v1
	v_mov_b32_e32 v3, v1
	v_mov_b32_e32 v0, v1
	v_mov_b64_e32 v[4:5], v[2:3]
	v_add_u32_e32 v21, 32, v7
	v_mov_b64_e32 v[2:3], v[0:1]
	v_mov_b32_e32 v116, 0
	v_mov_b32_e32 v117, 0
	v_mov_b32_e32 v118, 0
	v_mov_b32_e32 v119, 0
	v_mov_b32_e32 v140, 1.0
	s_and_saveexec_b64 s[8:9], s[4:5]
	s_cbranch_execz .LBB0_1274
	v_ashrrev_i32_e32 v0, 31, v21
	v_mul_lo_u32 v4, s19, v21
	v_mul_lo_u32 v0, s18, v0
	v_mad_u64_u32 v[2:3], s[54:55], s18, v21, 0
	v_add3_u32 v3, v3, v0, v4
	v_lshl_add_u64 v[2:3], v[2:3], 2, v[12:13]
	global_load_dwordx4 v[116:119], v[2:3], off nt
.LBB0_1274:
	s_or_b64 exec, exec, s[8:9]
	s_and_b64 vcc, exec, s[6:7]
	s_cbranch_vccnz .LBB0_1278
	v_cmp_le_i32_e32 vcc, s44, v21
	v_cmp_gt_i32_e64 s[8:9], s42, v21
	s_and_b64 s[54:55], vcc, s[8:9]
	s_and_saveexec_b64 s[8:9], s[54:55]
	s_cbranch_execz .LBB0_1277
	v_subrev_u32_e32 v0, s44, v21
	v_lshl_add_u64 v[22:23], v[0:1], 2, v[10:11]
	global_load_dword v140, v[22:23], off

.LBB0_1278:
	v_add_u32_e32 v0, 0x1080, v20
	v_add_u32_e32 v0, 0x1088, v20
	v_mov_b32_e32 v2, v1
	v_mov_b32_e32 v3, v1
	v_mov_b32_e32 v0, v1
	v_mov_b64_e32 v[4:5], v[2:3]
	v_add_u32_e32 v21, 40, v7
	v_mov_b64_e32 v[2:3], v[0:1]
	v_mov_b32_e32 v120, 0
	v_mov_b32_e32 v121, 0
	v_mov_b32_e32 v122, 0
	v_mov_b32_e32 v123, 0
	v_mov_b32_e32 v142, 1.0
	s_and_saveexec_b64 s[8:9], s[4:5]
	s_cbranch_execz .LBB0_1280
	v_ashrrev_i32_e32 v0, 31, v21
	v_mul_lo_u32 v4, s19, v21
	v_mul_lo_u32 v0, s18, v0
	v_mad_u64_u32 v[2:3], s[54:55], s18, v21, 0
	v_add3_u32 v3, v3, v0, v4
	v_lshl_add_u64 v[2:3], v[2:3], 2, v[12:13]
	global_load_dwordx4 v[120:123], v[2:3], off nt
.LBB0_1280:
	s_or_b64 exec, exec, s[8:9]
	s_and_b64 vcc, exec, s[6:7]
	s_cbranch_vccnz .LBB0_1284
	v_cmp_le_i32_e32 vcc, s44, v21
	v_cmp_gt_i32_e64 s[8:9], s42, v21
	s_and_b64 s[54:55], vcc, s[8:9]
	s_and_saveexec_b64 s[8:9], s[54:55]
	s_cbranch_execz .LBB0_1283
	v_subrev_u32_e32 v0, s44, v21
	v_lshl_add_u64 v[22:23], v[0:1], 2, v[10:11]
	global_load_dword v142, v[22:23], off

.LBB0_1284:
	v_add_u32_e32 v0, 0x14a0, v20
	v_add_u32_e32 v0, 0x14a8, v20
	v_mov_b32_e32 v2, v1
	v_mov_b32_e32 v3, v1
	v_mov_b32_e32 v0, v1
	v_mov_b64_e32 v[4:5], v[2:3]
	v_add_u32_e32 v21, 48, v7
	v_mov_b64_e32 v[2:3], v[0:1]
	v_mov_b32_e32 v124, 0
	v_mov_b32_e32 v125, 0
	v_mov_b32_e32 v126, 0
	v_mov_b32_e32 v127, 0
	v_mov_b32_e32 v144, 1.0
	s_and_saveexec_b64 s[8:9], s[4:5]
	s_cbranch_execz .LBB0_1286
	v_ashrrev_i32_e32 v0, 31, v21
	v_mul_lo_u32 v4, s19, v21
	v_mul_lo_u32 v0, s18, v0
	v_mad_u64_u32 v[2:3], s[54:55], s18, v21, 0
	v_add3_u32 v3, v3, v0, v4
	v_lshl_add_u64 v[2:3], v[2:3], 2, v[12:13]
	global_load_dwordx4 v[124:127], v[2:3], off nt
.LBB0_1286:
	s_or_b64 exec, exec, s[8:9]
	s_and_b64 vcc, exec, s[6:7]
	s_cbranch_vccnz .LBB0_1290
	v_cmp_le_i32_e32 vcc, s44, v21
	v_cmp_gt_i32_e64 s[8:9], s42, v21
	s_and_b64 s[54:55], vcc, s[8:9]
	s_and_saveexec_b64 s[8:9], s[54:55]
	s_cbranch_execz .LBB0_1289
	v_subrev_u32_e32 v0, s44, v21
	v_lshl_add_u64 v[22:23], v[0:1], 2, v[10:11]
	global_load_dword v144, v[22:23], off

.LBB0_1290:
	v_add_u32_e32 v0, 0x18c0, v20
	v_add_u32_e32 v0, 0x18c8, v20
	v_mov_b32_e32 v2, v1
	v_mov_b32_e32 v3, v1
	v_mov_b32_e32 v0, v1
	v_mov_b64_e32 v[4:5], v[2:3]
	v_add_u32_e32 v7, 56, v7
	v_mov_b64_e32 v[2:3], v[0:1]
	v_mov_b32_e32 v128, 0
	v_mov_b32_e32 v129, 0
	v_mov_b32_e32 v130, 0
	v_mov_b32_e32 v131, 0
	v_mov_b32_e32 v146, 1.0
	s_and_saveexec_b64 s[8:9], s[4:5]
	s_cbranch_execz .LBB0_1292
	v_ashrrev_i32_e32 v0, 31, v7
	v_mul_lo_u32 v4, s19, v7
	v_mul_lo_u32 v0, s18, v0
	v_mad_u64_u32 v[2:3], s[4:5], s18, v7, 0
	v_add3_u32 v3, v3, v0, v4
	v_lshl_add_u64 v[2:3], v[2:3], 2, v[12:13]
	global_load_dwordx4 v[128:131], v[2:3], off nt

.LBB0_1482:
	s_waitcnt vmcnt(0)
	v_pk_mul_f32 v[100:101], v[100:101], v[132:133] op_sel_hi:[1,0]
	v_pk_mul_f32 v[102:103], v[102:103], v[132:133] op_sel_hi:[1,0]
	v_pk_mul_f32 v[104:105], v[104:105], v[134:135] op_sel_hi:[1,0]
	v_pk_mul_f32 v[106:107], v[106:107], v[134:135] op_sel_hi:[1,0]
	v_pk_mul_f32 v[108:109], v[108:109], v[136:137] op_sel_hi:[1,0]
	v_pk_mul_f32 v[110:111], v[110:111], v[136:137] op_sel_hi:[1,0]
	v_pk_mul_f32 v[112:113], v[112:113], v[138:139] op_sel_hi:[1,0]
	v_pk_mul_f32 v[114:115], v[114:115], v[138:139] op_sel_hi:[1,0]
	v_pk_mul_f32 v[116:117], v[116:117], v[140:141] op_sel_hi:[1,0]
	v_pk_mul_f32 v[118:119], v[118:119], v[140:141] op_sel_hi:[1,0]
	v_pk_mul_f32 v[120:121], v[120:121], v[142:143] op_sel_hi:[1,0]
	v_pk_mul_f32 v[122:123], v[122:123], v[142:143] op_sel_hi:[1,0]
	v_pk_mul_f32 v[124:125], v[124:125], v[144:145] op_sel_hi:[1,0]
	v_pk_mul_f32 v[126:127], v[126:127], v[144:145] op_sel_hi:[1,0]
	v_pk_mul_f32 v[128:129], v[128:129], v[146:147] op_sel_hi:[1,0]
	v_pk_mul_f32 v[130:131], v[130:131], v[146:147] op_sel_hi:[1,0]
	ds_write2_b32 v21, v100, v101 offset1:1
	ds_write2_b32 v21, v102, v103 offset0:2 offset1:3
	v_add_u32_e32 v0, 0x420, v21
	ds_write2_b32 v0, v104, v105 offset1:1
	ds_write2_b32 v0, v106, v107 offset0:2 offset1:3
	v_add_u32_e32 v0, 0x840, v21
	ds_write2_b32 v0, v108, v109 offset1:1
	ds_write2_b32 v0, v110, v111 offset0:2 offset1:3
	v_add_u32_e32 v0, 0xc60, v21
	ds_write2_b32 v0, v112, v113 offset1:1
	ds_write2_b32 v0, v114, v115 offset0:2 offset1:3
	v_add_u32_e32 v0, 0x1080, v21
	ds_write2_b32 v0, v116, v117 offset1:1
	ds_write2_b32 v0, v118, v119 offset0:2 offset1:3
	v_add_u32_e32 v0, 0x14a0, v21
	ds_write2_b32 v0, v120, v121 offset1:1
	ds_write2_b32 v0, v122, v123 offset0:2 offset1:3
	v_add_u32_e32 v0, 0x18c0, v21
	ds_write2_b32 v0, v124, v125 offset1:1
	ds_write2_b32 v0, v126, v127 offset0:2 offset1:3
	v_add_u32_e32 v0, 0x1ce0, v21
	ds_write2_b32 v0, v128, v129 offset1:1
	ds_write2_b32 v0, v130, v131 offset0:2 offset1:3
	s_waitcnt lgkmcnt(0)
	ds_read2_b32 v[12:13], v20 offset0:33 offset1:41
	ds_read2_b32 v[22:23], v20 offset1:8
	v_add_u32_e32 v0, s52, v15
	ds_read2_b32 v[24:25], v20 offset0:66 offset1:74
	ds_read2_b32 v[26:27], v20 offset0:99 offset1:107
	ds_read2_b32 v[28:29], v20 offset0:132 offset1:140
	ds_read2_b32 v[30:31], v20 offset0:165 offset1:173
	ds_read2_b32 v[32:33], v20 offset0:198 offset1:206
	ds_read2_b32 v[34:35], v20 offset0:231 offset1:239
	v_ashrrev_i32_e32 v7, 31, v0
	s_waitcnt lgkmcnt(6)
	v_cvt_pk_bf16_f32 v2, v22, v12
	v_mul_lo_u32 v7, s20, v7
	v_mul_lo_u32 v12, s21, v0
	v_mad_u64_u32 v[36:37], s[4:5], s20, v0, 0
	s_ashr_i32 s23, s22, 31
	v_add3_u32 v37, v37, v7, v12
	v_lshl_add_u64 v[36:37], v[36:37], 1, s[16:17]
	s_lshl_b64 s[4:5], s[22:23], 1
	v_lshl_add_u64 v[36:37], v[36:37], 0, s[4:5]
	v_mov_b32_e32 v7, v1
	s_waitcnt lgkmcnt(4)
	v_cvt_pk_bf16_f32 v3, v24, v26
	s_waitcnt lgkmcnt(2)
	v_cvt_pk_bf16_f32 v4, v28, v30
	s_waitcnt lgkmcnt(0)
	v_cvt_pk_bf16_f32 v5, v32, v34
	v_lshl_add_u64 v[36:37], v[36:37], 0, v[6:7]
	v_add_u32_e32 v12, 8, v0
	global_store_dwordx4 v[36:37], v[2:5], off
	s_add_i32 s40, s40, s28
	s_add_i32 s47, s47, s48
	v_cvt_pk_bf16_f32 v2, v23, v13
	v_ashrrev_i32_e32 v13, 31, v12
	v_mul_lo_u32 v22, s20, v13
	v_mul_lo_u32 v23, s21, v12
	v_mad_u64_u32 v[12:13], s[6:7], s20, v12, 0
	v_add3_u32 v13, v13, v22, v23
	v_lshl_add_u64 v[12:13], v[12:13], 1, s[16:17]
	v_lshl_add_u64 v[12:13], v[12:13], 0, s[4:5]
	v_cvt_pk_bf16_f32 v3, v25, v27
	v_cvt_pk_bf16_f32 v4, v29, v31
	v_cvt_pk_bf16_f32 v5, v33, v35
	v_lshl_add_u64 v[12:13], v[12:13], 0, v[6:7]
	global_store_dwordx4 v[12:13], v[2:5], off
	ds_read2_b32 v[12:13], v20 offset0:16 offset1:24
	ds_read2_b32 v[22:23], v20 offset0:49 offset1:57
	ds_read2_b32 v[24:25], v20 offset0:82 offset1:90
	ds_read2_b32 v[26:27], v20 offset0:115 offset1:123
	ds_read2_b32 v[28:29], v20 offset0:148 offset1:156
	ds_read2_b32 v[30:31], v20 offset0:181 offset1:189
	ds_read2_b32 v[32:33], v20 offset0:214 offset1:222
	ds_read2_b32 v[34:35], v20 offset0:247 offset1:255
	s_add_i32 s50, s50, s51
	s_waitcnt lgkmcnt(6)
	v_cvt_pk_bf16_f32 v2, v12, v22
	v_add_u32_e32 v12, 16, v0
	v_ashrrev_i32_e32 v22, 31, v12
	s_waitcnt lgkmcnt(4)
	v_cvt_pk_bf16_f32 v3, v24, v26
	v_mul_lo_u32 v22, s20, v22
	v_mul_lo_u32 v24, s21, v12
	v_mad_u64_u32 v[36:37], s[6:7], s20, v12, 0
	v_add3_u32 v37, v37, v22, v24
	v_lshl_add_u64 v[36:37], v[36:37], 1, s[16:17]
	v_lshl_add_u64 v[36:37], v[36:37], 0, s[4:5]
	v_add_u32_e32 v0, 24, v0
	s_waitcnt lgkmcnt(2)
	v_cvt_pk_bf16_f32 v4, v28, v30
	s_waitcnt lgkmcnt(0)
	v_cvt_pk_bf16_f32 v5, v32, v34
	v_lshl_add_u64 v[36:37], v[36:37], 0, v[6:7]
	v_ashrrev_i32_e32 v12, 31, v0
	global_store_dwordx4 v[36:37], v[2:5], off
	v_mul_lo_u32 v22, s20, v12
	s_cmp_lt_i32 s40, s39
	v_cvt_pk_bf16_f32 v2, v13, v23
	v_mul_lo_u32 v23, s21, v0
	v_mad_u64_u32 v[12:13], s[6:7], s20, v0, 0
	v_add3_u32 v13, v13, v22, v23
	v_lshl_add_u64 v[12:13], v[12:13], 1, s[16:17]
	v_lshl_add_u64 v[12:13], v[12:13], 0, s[4:5]
	v_cvt_pk_bf16_f32 v3, v25, v27
	v_cvt_pk_bf16_f32 v4, v29, v31
	v_cvt_pk_bf16_f32 v5, v33, v35
	v_lshl_add_u64 v[12:13], v[12:13], 0, v[6:7]
	global_store_dwordx4 v[12:13], v[2:5], off
	s_waitcnt lgkmcnt(0)
	s_cbranch_scc0 .LBB0_1458

.LBB0_1590:
	s_waitcnt vmcnt(0)
	v_pk_mul_f32 v[100:101], v[100:101], v[132:133] op_sel_hi:[1,0]
	v_pk_mul_f32 v[102:103], v[102:103], v[132:133] op_sel_hi:[1,0]
	v_pk_mul_f32 v[104:105], v[104:105], v[134:135] op_sel_hi:[1,0]
	v_pk_mul_f32 v[106:107], v[106:107], v[134:135] op_sel_hi:[1,0]
	v_pk_mul_f32 v[108:109], v[108:109], v[136:137] op_sel_hi:[1,0]
	v_pk_mul_f32 v[110:111], v[110:111], v[136:137] op_sel_hi:[1,0]
	v_pk_mul_f32 v[112:113], v[112:113], v[138:139] op_sel_hi:[1,0]
	v_pk_mul_f32 v[114:115], v[114:115], v[138:139] op_sel_hi:[1,0]
	v_pk_mul_f32 v[116:117], v[116:117], v[140:141] op_sel_hi:[1,0]
	v_pk_mul_f32 v[118:119], v[118:119], v[140:141] op_sel_hi:[1,0]
	v_pk_mul_f32 v[120:121], v[120:121], v[142:143] op_sel_hi:[1,0]
	v_pk_mul_f32 v[122:123], v[122:123], v[142:143] op_sel_hi:[1,0]
	v_pk_mul_f32 v[124:125], v[124:125], v[144:145] op_sel_hi:[1,0]
	v_pk_mul_f32 v[126:127], v[126:127], v[144:145] op_sel_hi:[1,0]
	v_pk_mul_f32 v[128:129], v[128:129], v[146:147] op_sel_hi:[1,0]
	v_pk_mul_f32 v[130:131], v[130:131], v[146:147] op_sel_hi:[1,0]
	ds_write2_b32 v20, v100, v101 offset1:1
	ds_write2_b32 v20, v102, v103 offset0:2 offset1:3
	v_add_u32_e32 v0, 0x420, v20
	ds_write2_b32 v0, v104, v105 offset1:1
	ds_write2_b32 v0, v106, v107 offset0:2 offset1:3
	v_add_u32_e32 v0, 0x840, v20
	ds_write2_b32 v0, v108, v109 offset1:1
	ds_write2_b32 v0, v110, v111 offset0:2 offset1:3
	v_add_u32_e32 v0, 0xc60, v20
	ds_write2_b32 v0, v112, v113 offset1:1
	ds_write2_b32 v0, v114, v115 offset0:2 offset1:3
	v_add_u32_e32 v0, 0x1080, v20
	ds_write2_b32 v0, v116, v117 offset1:1
	ds_write2_b32 v0, v118, v119 offset0:2 offset1:3
	v_add_u32_e32 v0, 0x14a0, v20
	ds_write2_b32 v0, v120, v121 offset1:1
	ds_write2_b32 v0, v122, v123 offset0:2 offset1:3
	v_add_u32_e32 v0, 0x18c0, v20
	ds_write2_b32 v0, v124, v125 offset1:1
	ds_write2_b32 v0, v126, v127 offset0:2 offset1:3
	v_add_u32_e32 v0, 0x1ce0, v20
	ds_write2_b32 v0, v128, v129 offset1:1
	ds_write2_b32 v0, v130, v131 offset0:2 offset1:3
	s_waitcnt lgkmcnt(0)
	ds_read2_b32 v[12:13], v19 offset0:33 offset1:41
	ds_read2_b32 v[22:23], v19 offset1:8
	v_add_u32_e32 v0, s52, v14
	ds_read2_b32 v[24:25], v19 offset0:66 offset1:74
	ds_read2_b32 v[26:27], v19 offset0:99 offset1:107
	ds_read2_b32 v[28:29], v19 offset0:132 offset1:140
	ds_read2_b32 v[30:31], v19 offset0:165 offset1:173
	ds_read2_b32 v[32:33], v19 offset0:198 offset1:206
	ds_read2_b32 v[34:35], v19 offset0:231 offset1:239
	v_ashrrev_i32_e32 v7, 31, v0
	s_waitcnt lgkmcnt(6)
	v_cvt_pk_bf16_f32 v2, v22, v12
	v_mul_lo_u32 v7, s20, v7
	v_mul_lo_u32 v12, s21, v0
	v_mad_u64_u32 v[36:37], s[4:5], s20, v0, 0
	s_ashr_i32 s23, s22, 31
	v_add3_u32 v37, v37, v7, v12
	v_lshl_add_u64 v[36:37], v[36:37], 1, s[16:17]
	s_lshl_b64 s[4:5], s[22:23], 1
	v_lshl_add_u64 v[36:37], v[36:37], 0, s[4:5]
	v_mov_b32_e32 v7, v1
	s_waitcnt lgkmcnt(4)
	v_cvt_pk_bf16_f32 v3, v24, v26
	s_waitcnt lgkmcnt(2)
	v_cvt_pk_bf16_f32 v4, v28, v30
	s_waitcnt lgkmcnt(0)
	v_cvt_pk_bf16_f32 v5, v32, v34
	v_lshl_add_u64 v[36:37], v[36:37], 0, v[6:7]
	v_add_u32_e32 v12, 8, v0
	global_store_dwordx4 v[36:37], v[2:5], off
	v_mul_lo_u32 v22, s21, v12
	s_add_i32 s40, s40, s28
	v_cvt_pk_bf16_f32 v2, v23, v13
	v_ashrrev_i32_e32 v13, 31, v12
	v_mul_lo_u32 v21, s20, v13
	v_mad_u64_u32 v[12:13], s[6:7], s20, v12, 0
	v_add3_u32 v13, v13, v21, v22
	v_lshl_add_u64 v[12:13], v[12:13], 1, s[16:17]
	v_lshl_add_u64 v[12:13], v[12:13], 0, s[4:5]
	v_cvt_pk_bf16_f32 v3, v25, v27
	v_cvt_pk_bf16_f32 v4, v29, v31
	v_cvt_pk_bf16_f32 v5, v33, v35
	v_lshl_add_u64 v[12:13], v[12:13], 0, v[6:7]
	global_store_dwordx4 v[12:13], v[2:5], off
	ds_read2_b32 v[12:13], v19 offset0:16 offset1:24
	ds_read2_b32 v[22:23], v19 offset0:49 offset1:57
	ds_read2_b32 v[24:25], v19 offset0:82 offset1:90
	ds_read2_b32 v[26:27], v19 offset0:115 offset1:123
	ds_read2_b32 v[28:29], v19 offset0:148 offset1:156
	ds_read2_b32 v[30:31], v19 offset0:181 offset1:189
	ds_read2_b32 v[32:33], v19 offset0:214 offset1:222
	ds_read2_b32 v[34:35], v19 offset0:247 offset1:255
	s_add_i32 s47, s47, s48
	s_waitcnt lgkmcnt(6)
	v_cvt_pk_bf16_f32 v2, v12, v22
	v_add_u32_e32 v12, 16, v0
	v_ashrrev_i32_e32 v21, 31, v12
	v_mul_lo_u32 v21, s20, v21
	v_mul_lo_u32 v22, s21, v12
	v_mad_u64_u32 v[36:37], s[6:7], s20, v12, 0
	v_add3_u32 v37, v37, v21, v22
	v_lshl_add_u64 v[36:37], v[36:37], 1, s[16:17]
	v_lshl_add_u64 v[36:37], v[36:37], 0, s[4:5]
	v_add_u32_e32 v0, 24, v0
	s_waitcnt lgkmcnt(4)
	v_cvt_pk_bf16_f32 v3, v24, v26
	s_waitcnt lgkmcnt(2)
	v_cvt_pk_bf16_f32 v4, v28, v30
	s_waitcnt lgkmcnt(0)
	v_cvt_pk_bf16_f32 v5, v32, v34
	v_lshl_add_u64 v[36:37], v[36:37], 0, v[6:7]
	v_ashrrev_i32_e32 v12, 31, v0
	global_store_dwordx4 v[36:37], v[2:5], off
	v_mul_lo_u32 v21, s20, v12
	v_mul_lo_u32 v22, s21, v0
	v_cvt_pk_bf16_f32 v2, v13, v23
	v_mad_u64_u32 v[12:13], s[6:7], s20, v0, 0
	v_add3_u32 v13, v13, v21, v22
	v_lshl_add_u64 v[12:13], v[12:13], 1, s[16:17]
	v_lshl_add_u64 v[12:13], v[12:13], 0, s[4:5]
	v_cvt_pk_bf16_f32 v3, v25, v27
	v_cvt_pk_bf16_f32 v4, v29, v31
	v_cvt_pk_bf16_f32 v5, v33, v35
	v_lshl_add_u64 v[12:13], v[12:13], 0, v[6:7]
	global_store_dwordx4 v[12:13], v[2:5], off
	s_waitcnt lgkmcnt(0)
	s_add_i32 s50, s50, s51
	s_cmp_lt_i32 s40, s39
	s_cbranch_scc0 .LBB0_1566
